# LDS fragment-read bases hoisted out of the FF2 and out-proj K-loops as well
# speedup vs baseline: 1.0145x; 1.0017x over previous
; #define PG8_STAGE(bufoff, gbase, voff) do { _Pragma("unroll") for (int _i = 0; _i < 2; ++_i) \
;         __builtin_amdgcn_global_load_lds((const unsigned*)((const char*)(gbase) + (voff)[_i]), (LAS unsigned*)(lds + (bufoff) + ldsw + _i * 8192), 16, 0, 0); } while (0)
; #define PG8_LDA(dst, b, h) do { _Pragma("unroll") for (int m = 0; m < 4; ++m) _Pragma("unroll") for (int k = 0; k < 2; ++k) dst[m][k] = *(const LAS bf16x8*)(lds + PG8_SA(b, h) + aoff + m * 2048 + k * 1024); } while (0)
; #define PG8_LDB(dst, b, h) do { _Pragma("unroll") for (int n = 0; n < 2; ++n) _Pragma("unroll") for (int k = 0; k < 2; ++k) dst[n][k] = *(const LAS bf16x8*)(lds + PG8_SB(b, h) + boff + n * 2048 + k * 1024); } while (0)
; #define PG8_MMA(ai, bj, At, Bt) do { __builtin_amdgcn_s_setprio(1); _Pragma("unroll") for (int m = 0; m < 4; ++m) _Pragma("unroll") for (int n = 0; n < 2; ++n) _Pragma("unroll") for (int k = 0; k < 2; ++k) \
;         acc[ai][bj][m][n] = __builtin_amdgcn_mfma_f32_16x16x32_bf16(Bt[n][k], At[m][k], acc[ai][bj][m][n], 0, 0, 0); __builtin_amdgcn_s_setprio(0); } while (0)
; template <class Epi, class Sched>
; __device__ __forceinline__ void gemm_phase(LAS unsigned char* lds, const Gemm g, const Sched& S, const Epi& E) {
;     ...
;     for (;;) {
;         const bool has_next = S.next(ui + 1, nxt);
;         const char* nA = has_next ? (const char*)g.A + (size_t)nxt.pm * tstep : cA; const char* nB = has_next ? (const char*)g.Bt + (size_t)nxt.pn * tstep : cB;
;         for (int t = 0; t < nt; t += 2) {
;             const bool last = (t == nt - 2);
;             const char* a1 = cA + (size_t)(t + 1) * kstep;
;             const char* a2 = last ? nA : cA + (size_t)(t + 2) * kstep; const char* b2 = last ? nB : cB + (size_t)(t + 2) * kstep;
;             const char* a3 = a2 + kstep; const char* b3 = b2 + kstep;
;             if (last && has_next) S.a_ready(nxt);
;             PG8_LDB(B0, 0, 0); PG8_SCHED; PG8_LDA(At, 0, 0); PG8_STAGE(PG8_SA(1, 1), a1 + hstep, voffA);
;             PG8_WAIT_L(8); PG8_BAR; PG8_WAIT_L(0); PG8_MMA(0, 0, At, B0); PG8_BAR; PG8_SCHED;
;     ...
; #pragma unroll
;         for (int a = 0; a < 2; ++a)
; #pragma unroll
;             for (int b = 0; b < 2; ++b)
; #pragma unroll
;                 for (int m = 0; m < 4; ++m)
; #pragma unroll
;                     for (int n = 0; n < 2; ++n) acc[a][b][m][n] = (f32x4){0.f, 0.f, 0.f, 0.f};
.LBB0_1122:
	v_readlane_b32 s12, v253, 24
	v_readlane_b32 s13, v253, 25
	s_ashr_i32 s9, s8, 31
	s_mov_b32 s42, -2
	v_mov_b64_e32 v[2:3], s[12:13]
	v_cmp_lt_i64_e32 vcc, s[10:11], v[2:3]
	s_lshl_b64 s[10:11], s[8:9], 20
	s_add_u32 s10, s56, s10
	s_addc_u32 s11, s57, s11
	s_and_b64 s[12:13], vcc, exec
	s_cselect_b32 s3, s11, s19
	s_cselect_b32 s9, s10, s18
	s_ashr_i32 s1, s0, 31
	s_lshl_b64 s[12:13], s[0:1], 20
	s_add_u32 s12, s28, s12
	s_addc_u32 s13, s29, s13
	s_and_b64 s[22:23], vcc, exec
	s_cselect_b32 s1, s13, s21
	s_cselect_b32 s15, s12, s20
	s_add_u32 s17, s20, 0x100
	v_mov_b32_e32 v2, 0
	s_addc_u32 s41, s21, 0
	v_mov_b32_e32 v3, v2
	v_mov_b32_e32 v4, v2
	v_mov_b32_e32 v5, v2
	v_mov_b32_e32 v6, v2
	v_mov_b32_e32 v7, v2
	v_mov_b32_e32 v8, v2
	v_mov_b32_e32 v9, v2
	v_mov_b32_e32 v18, v2
	v_mov_b32_e32 v19, v2
	v_mov_b32_e32 v20, v2
	v_mov_b32_e32 v21, v2
	v_mov_b32_e32 v22, v2
	v_mov_b32_e32 v23, v2
	v_mov_b32_e32 v24, v2
	v_mov_b32_e32 v25, v2
	v_mov_b32_e32 v34, v2
	v_mov_b32_e32 v35, v2
	v_mov_b32_e32 v36, v2
	v_mov_b32_e32 v37, v2
	v_mov_b32_e32 v38, v2
	v_mov_b32_e32 v39, v2
	v_mov_b32_e32 v40, v2
	v_mov_b32_e32 v41, v2
	v_mov_b32_e32 v50, v2
	v_mov_b32_e32 v51, v2
	v_mov_b32_e32 v52, v2
	v_mov_b32_e32 v53, v2
	v_mov_b32_e32 v54, v2
	v_mov_b32_e32 v55, v2
	v_mov_b32_e32 v56, v2
	v_mov_b32_e32 v57, v2
	v_mov_b32_e32 v10, v2
	v_mov_b32_e32 v11, v2
	v_mov_b32_e32 v12, v2
	v_mov_b32_e32 v13, v2
	v_mov_b32_e32 v14, v2
	v_mov_b32_e32 v15, v2
	v_mov_b32_e32 v16, v2
	v_mov_b32_e32 v17, v2
	v_mov_b32_e32 v26, v2
	v_mov_b32_e32 v27, v2
	v_mov_b32_e32 v28, v2
	v_mov_b32_e32 v29, v2
	v_mov_b32_e32 v30, v2
	v_mov_b32_e32 v31, v2
	v_mov_b32_e32 v32, v2
	v_mov_b32_e32 v33, v2
	v_mov_b32_e32 v42, v2
	v_mov_b32_e32 v43, v2
	v_mov_b32_e32 v44, v2
	v_mov_b32_e32 v45, v2
	v_mov_b32_e32 v46, v2
	v_mov_b32_e32 v47, v2
	v_mov_b32_e32 v48, v2
	v_mov_b32_e32 v49, v2
	v_mov_b32_e32 v58, v2
	v_mov_b32_e32 v59, v2
	v_mov_b32_e32 v60, v2
	v_mov_b32_e32 v61, v2
	v_mov_b32_e32 v62, v2
	v_mov_b32_e32 v63, v2
	v_mov_b32_e32 v64, v2
	v_mov_b32_e32 v65, v2
	v_mov_b32_e32 v66, v2
	v_mov_b32_e32 v67, v2
	v_mov_b32_e32 v68, v2
	v_mov_b32_e32 v69, v2
	v_mov_b32_e32 v70, v2
	v_mov_b32_e32 v71, v2
	v_mov_b32_e32 v72, v2
	v_mov_b32_e32 v73, v2
	v_mov_b32_e32 v82, v2
	v_mov_b32_e32 v83, v2
	v_mov_b32_e32 v84, v2
	v_mov_b32_e32 v85, v2
	v_mov_b32_e32 v86, v2
	v_mov_b32_e32 v87, v2
	v_mov_b32_e32 v88, v2
	v_mov_b32_e32 v89, v2
	v_mov_b32_e32 v98, v2
	v_mov_b32_e32 v99, v2
	v_mov_b32_e32 v100, v2
	v_mov_b32_e32 v101, v2
	v_mov_b32_e32 v102, v2
	v_mov_b32_e32 v103, v2
	v_mov_b32_e32 v104, v2
	v_mov_b32_e32 v105, v2
	v_mov_b32_e32 v114, v2
	v_mov_b32_e32 v115, v2
	v_mov_b32_e32 v116, v2
	v_mov_b32_e32 v117, v2
	v_mov_b32_e32 v118, v2
	v_mov_b32_e32 v119, v2
	v_mov_b32_e32 v120, v2
	v_mov_b32_e32 v121, v2
	v_mov_b32_e32 v74, v2
	v_mov_b32_e32 v75, v2
	v_mov_b32_e32 v76, v2
	v_mov_b32_e32 v77, v2
	v_mov_b32_e32 v78, v2
	v_mov_b32_e32 v79, v2
	v_mov_b32_e32 v80, v2
	v_mov_b32_e32 v81, v2
	v_mov_b32_e32 v90, v2
	v_mov_b32_e32 v91, v2
	v_mov_b32_e32 v92, v2
	v_mov_b32_e32 v93, v2
	v_mov_b32_e32 v94, v2
	v_mov_b32_e32 v95, v2
	v_mov_b32_e32 v96, v2
	v_mov_b32_e32 v97, v2
	v_mov_b32_e32 v106, v2
	v_mov_b32_e32 v107, v2
	v_mov_b32_e32 v108, v2
	v_mov_b32_e32 v109, v2
	v_mov_b32_e32 v110, v2
	v_mov_b32_e32 v111, v2
	v_mov_b32_e32 v112, v2
	v_mov_b32_e32 v113, v2
	v_mov_b32_e32 v122, v2
	v_mov_b32_e32 v123, v2
	v_mov_b32_e32 v124, v2
	v_mov_b32_e32 v125, v2
	v_mov_b32_e32 v126, v2
	v_mov_b32_e32 v127, v2
	v_mov_b32_e32 v128, v2
	v_mov_b32_e32 v129, v2
	v_readlane_b32 s44, v253, 6
	s_mov_b64 s[46:47], 0x80
	v_add_u32_e32 v209, 0x14000, v151
	v_add_u32_e32 v210, 0x18000, v151
	v_add_u32_e32 v211, 0x1c000, v151
	v_add_u32_e32 v208, s44, v151
.LBB0_1123:
	s_nop 0
	ds_read_b128 v[138:141], v208
	ds_read_b128 v[142:145], v208 offset:1024
	ds_read_b128 v[146:149], v208 offset:2048
	ds_read_b128 v[154:157], v208 offset:3072
	s_add_u32 s20, s18, 0x100
	s_addc_u32 s21, s19, 0
	s_cmp_eq_u32 s42, 28
	s_cselect_b32 s25, s3, s21
	s_cselect_b32 s24, s9, s20
	s_cselect_b32 s23, s1, s41
	s_cselect_b32 s22, s15, s17
	s_add_i32 m0, s31, 0xc000
	ds_read_b128 v[158:161], v153
	ds_read_b128 v[162:165], v153 offset:1024
	ds_read_b128 v[166:169], v153 offset:2048
	ds_read_b128 v[170:173], v153 offset:3072
	ds_read_b128 v[174:177], v153 offset:4096
	ds_read_b128 v[178:181], v153 offset:5120
	ds_read_b128 v[182:185], v153 offset:6144
	ds_read_b128 v[186:189], v153 offset:7168
	global_load_lds_dwordx4 v134, s[18:19]
	s_add_i32 m0, s31, 0xe000
	s_nop 0
	global_load_lds_dwordx4 v136, s[18:19]
	s_waitcnt lgkmcnt(8)
	s_barrier
	s_waitcnt lgkmcnt(0)
	v_mfma_f32_16x16x32_bf16 v[126:129], v[138:141], v[158:161], v[126:129]
	v_mfma_f32_16x16x32_bf16 v[122:125], v[146:149], v[158:161], v[122:125]
	v_mfma_f32_16x16x32_bf16 v[110:113], v[138:141], v[166:169], v[110:113]
	v_mfma_f32_16x16x32_bf16 v[106:109], v[146:149], v[166:169], v[106:109]
	v_mfma_f32_16x16x32_bf16 v[94:97], v[138:141], v[174:177], v[94:97]
	v_mfma_f32_16x16x32_bf16 v[90:93], v[146:149], v[174:177], v[90:93]
	v_mfma_f32_16x16x32_bf16 v[78:81], v[138:141], v[182:185], v[78:81]
	v_mfma_f32_16x16x32_bf16 v[74:77], v[146:149], v[182:185], v[74:77]
	v_mfma_f32_16x16x32_bf16 v[126:129], v[142:145], v[162:165], v[126:129]
	v_mfma_f32_16x16x32_bf16 v[122:125], v[154:157], v[162:165], v[122:125]
	v_mfma_f32_16x16x32_bf16 v[110:113], v[142:145], v[170:173], v[110:113]
	v_mfma_f32_16x16x32_bf16 v[106:109], v[154:157], v[170:173], v[106:109]
	v_mfma_f32_16x16x32_bf16 v[94:97], v[142:145], v[178:181], v[94:97]
	v_mfma_f32_16x16x32_bf16 v[90:93], v[154:157], v[178:181], v[90:93]
	v_mfma_f32_16x16x32_bf16 v[78:81], v[142:145], v[186:189], v[78:81]
	v_mfma_f32_16x16x32_bf16 v[74:77], v[154:157], v[186:189], v[74:77]
	s_barrier
; #define PG8_STAGE(bufoff, gbase, voff) do { _Pragma("unroll") for (int _i = 0; _i < 2; ++_i) \
;         __builtin_amdgcn_global_load_lds((const unsigned*)((const char*)(gbase) + (voff)[_i]), (LAS unsigned*)(lds + (bufoff) + ldsw + _i * 8192), 16, 0, 0); } while (0)
; #define PG8_LDA(dst, b, h) do { _Pragma("unroll") for (int m = 0; m < 4; ++m) _Pragma("unroll") for (int k = 0; k < 2; ++k) dst[m][k] = *(const LAS bf16x8*)(lds + PG8_SA(b, h) + aoff + m * 2048 + k * 1024); } while (0)
; #define PG8_LDB(dst, b, h) do { _Pragma("unroll") for (int n = 0; n < 2; ++n) _Pragma("unroll") for (int k = 0; k < 2; ++k) dst[n][k] = *(const LAS bf16x8*)(lds + PG8_SB(b, h) + boff + n * 2048 + k * 1024); } while (0)
; #define PG8_MMA(ai, bj, At, Bt) do { __builtin_amdgcn_s_setprio(1); _Pragma("unroll") for (int m = 0; m < 4; ++m) _Pragma("unroll") for (int n = 0; n < 2; ++n) _Pragma("unroll") for (int k = 0; k < 2; ++k) \
;         acc[ai][bj][m][n] = __builtin_amdgcn_mfma_f32_16x16x32_bf16(Bt[n][k], At[m][k], acc[ai][bj][m][n], 0, 0, 0); __builtin_amdgcn_s_setprio(0); } while (0)
; #define PG8_WAIT_V(n) asm volatile("s_waitcnt vmcnt(" #n ")" ::: "memory")
; #define PG8_WAIT_L(n) asm volatile("s_waitcnt lgkmcnt(" #n ")" ::: "memory")
; #define PG8_BAR __builtin_amdgcn_s_barrier()
; #define PG8_SCHED __builtin_amdgcn_sched_barrier(0)
; template <class Epi, class Sched>
; __device__ __forceinline__ void gemm_phase(LAS unsigned char* lds, const Gemm g, const Sched& S, const Epi& E) {
;     ...
;             PG8_WAIT_L(8); PG8_BAR; PG8_WAIT_L(0); PG8_MMA(0, 0, At, B0); PG8_BAR; PG8_SCHED;
;             PG8_LDB(B1, 0, 1); PG8_STAGE(PG8_SB(0, 0), b2, voffB);
;             PG8_BAR; PG8_WAIT_L(0); PG8_MMA(0, 1, At, B1); PG8_BAR;
;             PG8_LDA(At, 0, 1); PG8_STAGE(PG8_SA(0, 0), a2, voffA);
;             PG8_BAR; PG8_WAIT_L(0); PG8_MMA(1, 0, At, B0); PG8_BAR; PG8_SCHED;
;             PG8_STAGE(PG8_SB(0, 1), b2 + hstep, voffB);
;             PG8_WAIT_V(6); PG8_BAR; PG8_MMA(1, 1, At, B1); PG8_BAR;
;             PG8_LDB(B0, 1, 0); PG8_SCHED; PG8_LDA(At, 1, 0); PG8_STAGE(PG8_SA(0, 1), a2 + hstep, voffA);
;             PG8_WAIT_L(8); PG8_BAR; PG8_WAIT_L(0); PG8_MMA(0, 0, At, B0); PG8_BAR; PG8_SCHED;
	s_add_i32 s43, 0, 0x14000
	s_add_i32 s18, s44, s30
	s_mov_b32 m0, s18
	ds_read_b128 v[190:193], v209
	ds_read_b128 v[194:197], v209 offset:1024
	ds_read_b128 v[198:201], v209 offset:2048
	ds_read_b128 v[202:205], v209 offset:3072
	global_load_lds_dwordx4 v130, s[22:23]
	s_add_i32 m0, s18, 0x2000
	s_nop 0
	global_load_lds_dwordx4 v132, s[22:23]
	s_barrier
	s_waitcnt lgkmcnt(0)
	v_mfma_f32_16x16x32_bf16 v[118:121], v[190:193], v[158:161], v[118:121]
	v_mfma_f32_16x16x32_bf16 v[114:117], v[198:201], v[158:161], v[114:117]
	v_mfma_f32_16x16x32_bf16 v[102:105], v[190:193], v[166:169], v[102:105]
	v_mfma_f32_16x16x32_bf16 v[98:101], v[198:201], v[166:169], v[98:101]
	v_mfma_f32_16x16x32_bf16 v[86:89], v[190:193], v[174:177], v[86:89]
	v_mfma_f32_16x16x32_bf16 v[82:85], v[198:201], v[174:177], v[82:85]
	v_mfma_f32_16x16x32_bf16 v[70:73], v[190:193], v[182:185], v[70:73]
	v_mfma_f32_16x16x32_bf16 v[66:69], v[198:201], v[182:185], v[66:69]
	v_mfma_f32_16x16x32_bf16 v[118:121], v[194:197], v[162:165], v[118:121]
	v_mfma_f32_16x16x32_bf16 v[114:117], v[202:205], v[162:165], v[114:117]
	v_mfma_f32_16x16x32_bf16 v[102:105], v[194:197], v[170:173], v[102:105]
	v_mfma_f32_16x16x32_bf16 v[98:101], v[202:205], v[170:173], v[98:101]
	v_mfma_f32_16x16x32_bf16 v[86:89], v[194:197], v[178:181], v[86:89]
	v_mfma_f32_16x16x32_bf16 v[82:85], v[202:205], v[178:181], v[82:85]
	v_mfma_f32_16x16x32_bf16 v[70:73], v[194:197], v[186:189], v[70:73]
	v_mfma_f32_16x16x32_bf16 v[66:69], v[202:205], v[186:189], v[66:69]
	s_mov_b32 m0, s31
	s_add_u32 s46, s24, 0x80
	s_addc_u32 s47, s25, 0
	s_barrier
	ds_read_b128 v[158:161], v153 offset:16384
	ds_read_b128 v[162:165], v153 offset:17408
	ds_read_b128 v[166:169], v153 offset:18432
	ds_read_b128 v[170:173], v153 offset:19456
	ds_read_b128 v[174:177], v153 offset:20480
	ds_read_b128 v[178:181], v153 offset:21504
	ds_read_b128 v[182:185], v153 offset:22528
	ds_read_b128 v[186:189], v153 offset:23552
	global_load_lds_dwordx4 v130, s[24:25]
	s_mov_b32 m0, s34
	s_nop 0
	global_load_lds_dwordx4 v132, s[24:25]
	s_barrier
	s_waitcnt lgkmcnt(0)
	v_mfma_f32_16x16x32_bf16 v[62:65], v[138:141], v[158:161], v[62:65]
	v_mfma_f32_16x16x32_bf16 v[58:61], v[146:149], v[158:161], v[58:61]
	v_mfma_f32_16x16x32_bf16 v[46:49], v[138:141], v[166:169], v[46:49]
	v_mfma_f32_16x16x32_bf16 v[42:45], v[146:149], v[166:169], v[42:45]
	v_mfma_f32_16x16x32_bf16 v[30:33], v[138:141], v[174:177], v[30:33]
	v_mfma_f32_16x16x32_bf16 v[26:29], v[146:149], v[174:177], v[26:29]
	v_mfma_f32_16x16x32_bf16 v[14:17], v[138:141], v[182:185], v[14:17]
	v_mfma_f32_16x16x32_bf16 v[10:13], v[146:149], v[182:185], v[10:13]
	v_mfma_f32_16x16x32_bf16 v[62:65], v[142:145], v[162:165], v[62:65]
	v_mfma_f32_16x16x32_bf16 v[58:61], v[154:157], v[162:165], v[58:61]
	v_mfma_f32_16x16x32_bf16 v[46:49], v[142:145], v[170:173], v[46:49]
	v_mfma_f32_16x16x32_bf16 v[42:45], v[154:157], v[170:173], v[42:45]
	v_mfma_f32_16x16x32_bf16 v[30:33], v[142:145], v[178:181], v[30:33]
	v_mfma_f32_16x16x32_bf16 v[26:29], v[154:157], v[178:181], v[26:29]
	v_mfma_f32_16x16x32_bf16 v[14:17], v[142:145], v[186:189], v[14:17]
	v_mfma_f32_16x16x32_bf16 v[10:13], v[154:157], v[186:189], v[10:13]
	s_barrier
	s_add_u32 s18, s22, 0x80000
	s_addc_u32 s19, s23, 0
	s_add_i32 s43, s43, s30
	s_mov_b32 m0, s43
	s_nop 0
	global_load_lds_dwordx4 v130, s[18:19]
	s_add_i32 m0, s43, 0x2000
	s_nop 0
	global_load_lds_dwordx4 v132, s[18:19]
	s_waitcnt vmcnt(6)
	s_barrier
	v_mfma_f32_16x16x32_bf16 v[54:57], v[190:193], v[158:161], v[54:57]
	v_mfma_f32_16x16x32_bf16 v[50:53], v[198:201], v[158:161], v[50:53]
	v_mfma_f32_16x16x32_bf16 v[38:41], v[190:193], v[166:169], v[38:41]
	v_mfma_f32_16x16x32_bf16 v[34:37], v[198:201], v[166:169], v[34:37]
	v_mfma_f32_16x16x32_bf16 v[22:25], v[190:193], v[174:177], v[22:25]
	v_mfma_f32_16x16x32_bf16 v[18:21], v[198:201], v[174:177], v[18:21]
	v_mfma_f32_16x16x32_bf16 v[6:9], v[190:193], v[182:185], v[6:9]
	v_mfma_f32_16x16x32_bf16 v[2:5], v[198:201], v[182:185], v[2:5]
	v_mfma_f32_16x16x32_bf16 v[54:57], v[194:197], v[162:165], v[54:57]
	v_mfma_f32_16x16x32_bf16 v[50:53], v[202:205], v[162:165], v[50:53]
	v_mfma_f32_16x16x32_bf16 v[38:41], v[194:197], v[170:173], v[38:41]
	v_mfma_f32_16x16x32_bf16 v[34:37], v[202:205], v[170:173], v[34:37]
	v_mfma_f32_16x16x32_bf16 v[22:25], v[194:197], v[178:181], v[22:25]
	v_mfma_f32_16x16x32_bf16 v[18:21], v[202:205], v[178:181], v[18:21]
	v_mfma_f32_16x16x32_bf16 v[6:9], v[194:197], v[186:189], v[6:9]
	v_mfma_f32_16x16x32_bf16 v[2:5], v[202:205], v[186:189], v[2:5]
	s_add_i32 s43, 0, 0x18000
	s_barrier
	ds_read_b128 v[138:141], v210
	ds_read_b128 v[142:145], v210 offset:1024
	ds_read_b128 v[146:149], v210 offset:2048
	ds_read_b128 v[154:157], v210 offset:3072
	s_add_u32 s18, s24, 0x80000
	s_addc_u32 s19, s25, 0
	s_mov_b32 m0, s35
	ds_read_b128 v[158:161], v153 offset:32768
	ds_read_b128 v[162:165], v153 offset:33792
	ds_read_b128 v[166:169], v153 offset:34816
	ds_read_b128 v[170:173], v153 offset:35840
	ds_read_b128 v[174:177], v153 offset:36864
	ds_read_b128 v[178:181], v153 offset:37888
	ds_read_b128 v[182:185], v153 offset:38912
	ds_read_b128 v[186:189], v153 offset:39936
	global_load_lds_dwordx4 v130, s[18:19]
	s_mov_b32 m0, s36
	s_nop 0
	global_load_lds_dwordx4 v132, s[18:19]
	s_waitcnt lgkmcnt(8)
	s_barrier
; #define PG8_STAGE(bufoff, gbase, voff) do { _Pragma("unroll") for (int _i = 0; _i < 2; ++_i) \
;         __builtin_amdgcn_global_load_lds((const unsigned*)((const char*)(gbase) + (voff)[_i]), (LAS unsigned*)(lds + (bufoff) + ldsw + _i * 8192), 16, 0, 0); } while (0)
; #define PG8_LDA(dst, b, h) do { _Pragma("unroll") for (int m = 0; m < 4; ++m) _Pragma("unroll") for (int k = 0; k < 2; ++k) dst[m][k] = *(const LAS bf16x8*)(lds + PG8_SA(b, h) + aoff + m * 2048 + k * 1024); } while (0)
; #define PG8_LDB(dst, b, h) do { _Pragma("unroll") for (int n = 0; n < 2; ++n) _Pragma("unroll") for (int k = 0; k < 2; ++k) dst[n][k] = *(const LAS bf16x8*)(lds + PG8_SB(b, h) + boff + n * 2048 + k * 1024); } while (0)
; #define PG8_MMA(ai, bj, At, Bt) do { __builtin_amdgcn_s_setprio(1); _Pragma("unroll") for (int m = 0; m < 4; ++m) _Pragma("unroll") for (int n = 0; n < 2; ++n) _Pragma("unroll") for (int k = 0; k < 2; ++k) \
;         acc[ai][bj][m][n] = __builtin_amdgcn_mfma_f32_16x16x32_bf16(Bt[n][k], At[m][k], acc[ai][bj][m][n], 0, 0, 0); __builtin_amdgcn_s_setprio(0); } while (0)
; #define PG8_WAIT_V(n) asm volatile("s_waitcnt vmcnt(" #n ")" ::: "memory")
; #define PG8_WAIT_L(n) asm volatile("s_waitcnt lgkmcnt(" #n ")" ::: "memory")
; #define PG8_BAR __builtin_amdgcn_s_barrier()
; #define PG8_SCHED __builtin_amdgcn_sched_barrier(0)
; template <class Epi, class Sched>
; __device__ __forceinline__ void gemm_phase(LAS unsigned char* lds, const Gemm g, const Sched& S, const Epi& E) {
;     ...
;             PG8_WAIT_L(8); PG8_BAR; PG8_WAIT_L(0); PG8_MMA(0, 0, At, B0); PG8_BAR; PG8_SCHED;
;             PG8_LDB(B1, 1, 1); PG8_STAGE(PG8_SB(1, 0), b3, voffB);
;             PG8_BAR; PG8_WAIT_L(0); PG8_MMA(0, 1, At, B1); PG8_BAR;
;             PG8_LDA(At, 1, 1); PG8_STAGE(PG8_SA(1, 0), a3, voffA);
;             PG8_BAR; PG8_WAIT_L(0); PG8_MMA(1, 0, At, B0); PG8_BAR; PG8_SCHED;
;             PG8_STAGE(PG8_SB(1, 1), b3 + hstep, voffB);
;             PG8_WAIT_V(6); PG8_BAR; PG8_MMA(1, 1, At, B1); PG8_BAR;
	s_waitcnt lgkmcnt(0)
	v_mfma_f32_16x16x32_bf16 v[126:129], v[138:141], v[158:161], v[126:129]
	v_mfma_f32_16x16x32_bf16 v[122:125], v[146:149], v[158:161], v[122:125]
	v_mfma_f32_16x16x32_bf16 v[110:113], v[138:141], v[166:169], v[110:113]
	v_mfma_f32_16x16x32_bf16 v[106:109], v[146:149], v[166:169], v[106:109]
	v_mfma_f32_16x16x32_bf16 v[94:97], v[138:141], v[174:177], v[94:97]
	v_mfma_f32_16x16x32_bf16 v[90:93], v[146:149], v[174:177], v[90:93]
	v_mfma_f32_16x16x32_bf16 v[78:81], v[138:141], v[182:185], v[78:81]
	v_mfma_f32_16x16x32_bf16 v[74:77], v[146:149], v[182:185], v[74:77]
	v_mfma_f32_16x16x32_bf16 v[126:129], v[142:145], v[162:165], v[126:129]
	v_mfma_f32_16x16x32_bf16 v[122:125], v[154:157], v[162:165], v[122:125]
	v_mfma_f32_16x16x32_bf16 v[110:113], v[142:145], v[170:173], v[110:113]
	v_mfma_f32_16x16x32_bf16 v[106:109], v[154:157], v[170:173], v[106:109]
	v_mfma_f32_16x16x32_bf16 v[94:97], v[142:145], v[178:181], v[94:97]
	v_mfma_f32_16x16x32_bf16 v[90:93], v[154:157], v[178:181], v[90:93]
	v_mfma_f32_16x16x32_bf16 v[78:81], v[142:145], v[186:189], v[78:81]
	v_mfma_f32_16x16x32_bf16 v[74:77], v[154:157], v[186:189], v[74:77]
	s_barrier
	s_add_i32 s24, 0, 0x1c000
	s_add_i32 s18, s43, s30
	s_add_u32 s48, s22, 0x80
	s_addc_u32 s49, s23, 0
	s_mov_b32 m0, s18
	ds_read_b128 v[190:193], v211
	ds_read_b128 v[194:197], v211 offset:1024
	ds_read_b128 v[198:201], v211 offset:2048
	ds_read_b128 v[202:205], v211 offset:3072
	global_load_lds_dwordx4 v130, s[48:49]
	s_add_i32 m0, s18, 0x2000
	s_nop 0
	global_load_lds_dwordx4 v132, s[48:49]
	s_barrier
	s_waitcnt lgkmcnt(0)
	v_mfma_f32_16x16x32_bf16 v[118:121], v[190:193], v[158:161], v[118:121]
	v_mfma_f32_16x16x32_bf16 v[114:117], v[198:201], v[158:161], v[114:117]
	v_mfma_f32_16x16x32_bf16 v[102:105], v[190:193], v[166:169], v[102:105]
	v_mfma_f32_16x16x32_bf16 v[98:101], v[198:201], v[166:169], v[98:101]
	v_mfma_f32_16x16x32_bf16 v[86:89], v[190:193], v[174:177], v[86:89]
	v_mfma_f32_16x16x32_bf16 v[82:85], v[198:201], v[174:177], v[82:85]
	v_mfma_f32_16x16x32_bf16 v[70:73], v[190:193], v[182:185], v[70:73]
	v_mfma_f32_16x16x32_bf16 v[66:69], v[198:201], v[182:185], v[66:69]
	v_mfma_f32_16x16x32_bf16 v[118:121], v[194:197], v[162:165], v[118:121]
	v_mfma_f32_16x16x32_bf16 v[114:117], v[202:205], v[162:165], v[114:117]
	v_mfma_f32_16x16x32_bf16 v[102:105], v[194:197], v[170:173], v[102:105]
	v_mfma_f32_16x16x32_bf16 v[98:101], v[202:205], v[170:173], v[98:101]
	v_mfma_f32_16x16x32_bf16 v[86:89], v[194:197], v[178:181], v[86:89]
	v_mfma_f32_16x16x32_bf16 v[82:85], v[202:205], v[178:181], v[82:85]
	v_mfma_f32_16x16x32_bf16 v[70:73], v[194:197], v[186:189], v[70:73]
	v_mfma_f32_16x16x32_bf16 v[66:69], v[202:205], v[186:189], v[66:69]
	s_mov_b32 m0, s38
	s_barrier
	ds_read_b128 v[158:161], v153 offset:49152
	ds_read_b128 v[162:165], v153 offset:50176
	ds_read_b128 v[166:169], v153 offset:51200
	ds_read_b128 v[170:173], v153 offset:52224
	ds_read_b128 v[174:177], v153 offset:53248
	ds_read_b128 v[178:181], v153 offset:54272
	ds_read_b128 v[182:185], v153 offset:55296
	ds_read_b128 v[186:189], v153 offset:56320
	global_load_lds_dwordx4 v130, s[46:47]
	s_mov_b32 m0, s39
	s_nop 0
	global_load_lds_dwordx4 v132, s[46:47]
	s_barrier
	s_waitcnt lgkmcnt(0)
	v_mfma_f32_16x16x32_bf16 v[62:65], v[138:141], v[158:161], v[62:65]
	v_mfma_f32_16x16x32_bf16 v[58:61], v[146:149], v[158:161], v[58:61]
	v_mfma_f32_16x16x32_bf16 v[46:49], v[138:141], v[166:169], v[46:49]
	v_mfma_f32_16x16x32_bf16 v[42:45], v[146:149], v[166:169], v[42:45]
	v_mfma_f32_16x16x32_bf16 v[30:33], v[138:141], v[174:177], v[30:33]
	v_mfma_f32_16x16x32_bf16 v[26:29], v[146:149], v[174:177], v[26:29]
	v_mfma_f32_16x16x32_bf16 v[14:17], v[138:141], v[182:185], v[14:17]
	v_mfma_f32_16x16x32_bf16 v[10:13], v[146:149], v[182:185], v[10:13]
	v_mfma_f32_16x16x32_bf16 v[62:65], v[142:145], v[162:165], v[62:65]
	v_mfma_f32_16x16x32_bf16 v[58:61], v[154:157], v[162:165], v[58:61]
	v_mfma_f32_16x16x32_bf16 v[46:49], v[142:145], v[170:173], v[46:49]
	v_mfma_f32_16x16x32_bf16 v[42:45], v[154:157], v[170:173], v[42:45]
	v_mfma_f32_16x16x32_bf16 v[30:33], v[142:145], v[178:181], v[30:33]
	v_mfma_f32_16x16x32_bf16 v[26:29], v[154:157], v[178:181], v[26:29]
	v_mfma_f32_16x16x32_bf16 v[14:17], v[142:145], v[186:189], v[14:17]
	v_mfma_f32_16x16x32_bf16 v[10:13], v[154:157], v[186:189], v[10:13]
	s_barrier
	s_add_u32 s18, s22, 0x80080
	s_addc_u32 s19, s23, 0
	s_add_i32 s22, s24, s30
	s_mov_b32 m0, s22
	s_nop 0
	global_load_lds_dwordx4 v130, s[18:19]
	s_add_i32 m0, s22, 0x2000
	s_nop 0
	global_load_lds_dwordx4 v132, s[18:19]
	s_waitcnt vmcnt(6)
	s_barrier
	v_mfma_f32_16x16x32_bf16 v[54:57], v[190:193], v[158:161], v[54:57]
	v_mfma_f32_16x16x32_bf16 v[50:53], v[198:201], v[158:161], v[50:53]
	v_mfma_f32_16x16x32_bf16 v[38:41], v[190:193], v[166:169], v[38:41]
	v_mfma_f32_16x16x32_bf16 v[34:37], v[198:201], v[166:169], v[34:37]
	v_mfma_f32_16x16x32_bf16 v[22:25], v[190:193], v[174:177], v[22:25]
	v_mfma_f32_16x16x32_bf16 v[18:21], v[198:201], v[174:177], v[18:21]
	v_mfma_f32_16x16x32_bf16 v[6:9], v[190:193], v[182:185], v[6:9]
	v_mfma_f32_16x16x32_bf16 v[2:5], v[198:201], v[182:185], v[2:5]
	v_mfma_f32_16x16x32_bf16 v[54:57], v[194:197], v[162:165], v[54:57]
	v_mfma_f32_16x16x32_bf16 v[50:53], v[202:205], v[162:165], v[50:53]
	v_mfma_f32_16x16x32_bf16 v[38:41], v[194:197], v[170:173], v[38:41]
	v_mfma_f32_16x16x32_bf16 v[34:37], v[202:205], v[170:173], v[34:37]
	v_mfma_f32_16x16x32_bf16 v[22:25], v[194:197], v[178:181], v[22:25]
	v_mfma_f32_16x16x32_bf16 v[18:21], v[202:205], v[178:181], v[18:21]
	v_mfma_f32_16x16x32_bf16 v[6:9], v[194:197], v[186:189], v[6:9]
	v_mfma_f32_16x16x32_bf16 v[2:5], v[202:205], v[186:189], v[2:5]
	s_add_i32 s42, s42, 2
	s_add_u32 s17, s17, 0x100
	s_addc_u32 s41, s41, 0
	s_cmp_gt_u32 s42, 29
	s_mov_b64 s[18:19], s[20:21]
	s_barrier
;     __device__ __forceinline__ void operator()(const f32x4 (&acc)[2][2][4][2], const pg8::Unit& u, int wr, int wc, int fr, int fq) const {
;         const int row0 = u.pm * 256 + wr * 64 + fr; const int col0 = u.pn * 256 + wc * 32 + 4 * fq;
; #pragma unroll
;         for (int ai = 0; ai < 2; ++ai)
; #pragma unroll
;             for (int m = 0; m < 4; ++m) { const int row = row0 + ai * 128 + m * 16;
;                 const float* ip; float* op; int b;
;                 if (row < ML_ROWS) { b = row >> 11; ip = xi + (size_t)row * D; op = xo + (size_t)row * D; }
;                 else { b = 8; ip = ci + (size_t)(row - ML_ROWS) * D; op = co + (size_t)(row - ML_ROWS) * D; }
;                 const float* gp = mod + (size_t)b * 12288 + slot * 2048;
; #pragma unroll
;                 for (int bj = 0; bj < 2; ++bj)
; #pragma unroll
;                     for (int n = 0; n < 2; ++n) { const int c = col0 + bj * 128 + n * 16;
;                         const f32x4 r = *(const f32x4*)(ip + c), g = *(const f32x4*)(gp + c);
;                         *(f32x4*)(op + c) = r + g * acc[ai][bj][m][n]; } }
	s_cbranch_scc0 .LBB0_1123
	s_lshl_b32 s1, s16, 8
	s_add_i32 s1, s1, s37
	v_readlane_b32 s44, v251, 0
	v_readlane_b32 s45, v251, 1
	v_readlane_b32 s46, v251, 2
	v_readlane_b32 s47, v251, 3
	v_readlane_b32 s48, v251, 4
	v_readlane_b32 s49, v251, 5
	v_readlane_b32 s50, v251, 6
	v_readlane_b32 s51, v251, 7
	v_readlane_b32 s22, v254, 4
	v_readlane_b32 s23, v254, 5
	v_readlane_b32 s20, v254, 6
	v_readlane_b32 s21, v254, 7
	v_readlane_b32 s18, v254, 2
	v_readlane_b32 s19, v254, 3
	s_add_i32 s3, s1, 0xffffc000
	s_ashr_i32 s15, s1, 11
	s_cmpk_lt_i32 s1, 0x4000
	s_cselect_b32 s22, s22, s20
	s_cselect_b32 s23, s23, s21
	s_cselect_b32 s20, s46, s60
	s_cselect_b32 s21, s47, s61
	s_cselect_b32 s3, s1, s3
	s_cselect_b32 s15, s15, 8
	s_mul_i32 s15, s15, 0xc000
	s_add_u32 s18, s18, s15
	s_addc_u32 s19, s19, 0
	s_add_u32 s18, s18, 0x4000
	s_addc_u32 s19, s19, 0
	v_add_u32_e32 v138, s3, v150
	v_lshl_or_b32 v139, s14, 8, v152
	v_lshlrev_b32_e32 v139, 2, v139
	v_lshl_or_b32 v138, v138, 13, v139
	v_add_u32_e32 v140, 0x20000, v138
	v_add_u32_e32 v141, 0x40000, v138
	v_add_u32_e32 v0, 0x60000, v138
	v_add_u32_e32 v210, 0x100000, v138
	v_add_u32_e32 v211, 0x120000, v138
	v_add_u32_e32 v220, 0x140000, v138
	global_load_dwordx4 v[154:157], v139, s[18:19]
	global_load_dwordx4 v[158:161], v139, s[18:19] offset:64
	global_load_dwordx4 v[162:165], v139, s[18:19] offset:512
	global_load_dwordx4 v[166:169], v139, s[18:19] offset:576
	v_add_u32_e32 v139, 0x160000, v138
	global_load_dwordx4 v[170:173], v138, s[22:23]
	global_load_dwordx4 v[174:177], v138, s[22:23] offset:64
	global_load_dwordx4 v[178:181], v138, s[22:23] offset:512
	global_load_dwordx4 v[182:185], v138, s[22:23] offset:576
	global_load_dwordx4 v[186:189], v140, s[22:23]
	global_load_dwordx4 v[190:193], v140, s[22:23] offset:64
	global_load_dwordx4 v[194:197], v140, s[22:23] offset:512
	global_load_dwordx4 v[198:201], v140, s[22:23] offset:576
	global_load_dwordx4 v[202:205], v141, s[22:23]
	global_load_dwordx4 v[206:209], v141, s[22:23] offset:64
	global_load_dwordx4 v[142:145], v141, s[22:23] offset:512
	global_load_dwordx4 v[146:149], v141, s[22:23] offset:576
	s_waitcnt vmcnt(8)
	v_pk_fma_f32 v[126:127], v[126:127], v[154:155], v[170:171]
	v_pk_fma_f32 v[128:129], v[128:129], v[156:157], v[172:173]
	v_pk_fma_f32 v[122:123], v[122:123], v[158:159], v[174:175]
	v_pk_fma_f32 v[124:125], v[124:125], v[160:161], v[176:177]
	v_pk_fma_f32 v[118:119], v[118:119], v[162:163], v[178:179]
	v_pk_fma_f32 v[120:121], v[120:121], v[164:165], v[180:181]
	v_pk_fma_f32 v[114:115], v[114:115], v[166:167], v[182:183]
	v_pk_fma_f32 v[116:117], v[116:117], v[168:169], v[184:185]
	global_store_dwordx4 v138, v[126:129], s[20:21]
	global_store_dwordx4 v138, v[122:125], s[20:21] offset:64
	global_store_dwordx4 v138, v[118:121], s[20:21] offset:512
	global_store_dwordx4 v138, v[114:117], s[20:21] offset:576
	global_load_dwordx4 v[170:173], v0, s[22:23]
	global_load_dwordx4 v[174:177], v0, s[22:23] offset:64
	global_load_dwordx4 v[178:181], v0, s[22:23] offset:512
	global_load_dwordx4 v[182:185], v0, s[22:23] offset:576
	s_waitcnt vmcnt(12)
	v_pk_fma_f32 v[110:111], v[110:111], v[154:155], v[186:187]
	v_pk_fma_f32 v[112:113], v[112:113], v[156:157], v[188:189]
	v_pk_fma_f32 v[106:107], v[106:107], v[158:159], v[190:191]
	v_pk_fma_f32 v[108:109], v[108:109], v[160:161], v[192:193]
	v_pk_fma_f32 v[102:103], v[102:103], v[162:163], v[194:195]
	v_pk_fma_f32 v[104:105], v[104:105], v[164:165], v[196:197]
	v_pk_fma_f32 v[98:99], v[98:99], v[166:167], v[198:199]
	v_pk_fma_f32 v[100:101], v[100:101], v[168:169], v[200:201]
	global_store_dwordx4 v140, v[110:113], s[20:21]
	global_store_dwordx4 v140, v[106:109], s[20:21] offset:64
	global_store_dwordx4 v140, v[102:105], s[20:21] offset:512
	global_store_dwordx4 v140, v[98:101], s[20:21] offset:576
	global_load_dwordx4 v[186:189], v210, s[22:23]
	global_load_dwordx4 v[190:193], v210, s[22:23] offset:64
	global_load_dwordx4 v[194:197], v210, s[22:23] offset:512
	global_load_dwordx4 v[198:201], v210, s[22:23] offset:576
	s_waitcnt vmcnt(16)
	v_pk_fma_f32 v[94:95], v[94:95], v[154:155], v[202:203]
	v_pk_fma_f32 v[96:97], v[96:97], v[156:157], v[204:205]
	v_pk_fma_f32 v[90:91], v[90:91], v[158:159], v[206:207]
	v_pk_fma_f32 v[92:93], v[92:93], v[160:161], v[208:209]
	v_pk_fma_f32 v[86:87], v[86:87], v[162:163], v[142:143]
	v_pk_fma_f32 v[88:89], v[88:89], v[164:165], v[144:145]
	v_pk_fma_f32 v[82:83], v[82:83], v[166:167], v[146:147]
	v_pk_fma_f32 v[84:85], v[84:85], v[168:169], v[148:149]
	global_store_dwordx4 v141, v[94:97], s[20:21]
	global_store_dwordx4 v141, v[90:93], s[20:21] offset:64
	global_store_dwordx4 v141, v[86:89], s[20:21] offset:512
	global_store_dwordx4 v141, v[82:85], s[20:21] offset:576
	global_load_dwordx4 v[202:205], v211, s[22:23]
	global_load_dwordx4 v[206:209], v211, s[22:23] offset:64
	global_load_dwordx4 v[142:145], v211, s[22:23] offset:512
	global_load_dwordx4 v[146:149], v211, s[22:23] offset:576
	s_waitcnt vmcnt(16)
; template <class Epi, class Sched>
; __device__ __forceinline__ void gemm_phase(LAS unsigned char* lds, const Gemm g, const Sched& S, const Epi& E) {
;     ...
;         E(acc, cur, wr, wc, fr, fq); S.done(cur);
;         if (!has_next) break;
; #pragma unroll
;         for (int a = 0; a < 2; ++a)
; #pragma unroll
;             for (int b = 0; b < 2; ++b)
; #pragma unroll
;                 for (int m = 0; m < 4; ++m)
; #pragma unroll
;                     for (int n = 0; n < 2; ++n) acc[a][b][m][n] = (f32x4){0.f, 0.f, 0.f, 0.f};
;         cur = nxt; cA = nA; cB = nB; ++ui;
;     __device__ __forceinline__ void operator()(const f32x4 (&acc)[2][2][4][2], const pg8::Unit& u, int wr, int wc, int fr, int fq) const {
;         const int row0 = u.pm * 256 + wr * 64 + fr; const int col0 = u.pn * 256 + wc * 32 + 4 * fq;
; #pragma unroll
;         for (int ai = 0; ai < 2; ++ai)
; #pragma unroll
;             for (int m = 0; m < 4; ++m) { const int row = row0 + ai * 128 + m * 16;
;                 const float* ip; float* op; int b;
;                 if (row < ML_ROWS) { b = row >> 11; ip = xi + (size_t)row * D; op = xo + (size_t)row * D; }
;                 else { b = 8; ip = ci + (size_t)(row - ML_ROWS) * D; op = co + (size_t)(row - ML_ROWS) * D; }
;                 const float* gp = mod + (size_t)b * 12288 + slot * 2048;
; #pragma unroll
;                 for (int bj = 0; bj < 2; ++bj)
; #pragma unroll
;                     for (int n = 0; n < 2; ++n) { const int c = col0 + bj * 128 + n * 16;
;                         const f32x4 r = *(const f32x4*)(ip + c), g = *(const f32x4*)(gp + c);
;                         *(f32x4*)(op + c) = r + g * acc[ai][bj][m][n]; } }
	v_pk_fma_f32 v[78:79], v[78:79], v[154:155], v[170:171]
	v_pk_fma_f32 v[80:81], v[80:81], v[156:157], v[172:173]
	v_pk_fma_f32 v[74:75], v[74:75], v[158:159], v[174:175]
	v_pk_fma_f32 v[76:77], v[76:77], v[160:161], v[176:177]
	v_pk_fma_f32 v[70:71], v[70:71], v[162:163], v[178:179]
	v_pk_fma_f32 v[72:73], v[72:73], v[164:165], v[180:181]
	v_pk_fma_f32 v[66:67], v[66:67], v[166:167], v[182:183]
	v_pk_fma_f32 v[68:69], v[68:69], v[168:169], v[184:185]
	global_store_dwordx4 v0, v[78:81], s[20:21]
	global_store_dwordx4 v0, v[74:77], s[20:21] offset:64
	global_store_dwordx4 v0, v[70:73], s[20:21] offset:512
	global_store_dwordx4 v0, v[66:69], s[20:21] offset:576
	global_load_dwordx4 v[170:173], v220, s[22:23]
	global_load_dwordx4 v[174:177], v220, s[22:23] offset:64
	global_load_dwordx4 v[178:181], v220, s[22:23] offset:512
	global_load_dwordx4 v[182:185], v220, s[22:23] offset:576
	s_waitcnt vmcnt(16)
	v_pk_fma_f32 v[62:63], v[62:63], v[154:155], v[186:187]
	v_pk_fma_f32 v[64:65], v[64:65], v[156:157], v[188:189]
	v_pk_fma_f32 v[58:59], v[58:59], v[158:159], v[190:191]
	v_pk_fma_f32 v[60:61], v[60:61], v[160:161], v[192:193]
	v_pk_fma_f32 v[54:55], v[54:55], v[162:163], v[194:195]
	v_pk_fma_f32 v[56:57], v[56:57], v[164:165], v[196:197]
	v_pk_fma_f32 v[50:51], v[50:51], v[166:167], v[198:199]
	v_pk_fma_f32 v[52:53], v[52:53], v[168:169], v[200:201]
	global_store_dwordx4 v210, v[62:65], s[20:21]
	global_store_dwordx4 v210, v[58:61], s[20:21] offset:64
	global_store_dwordx4 v210, v[54:57], s[20:21] offset:512
	global_store_dwordx4 v210, v[50:53], s[20:21] offset:576
	global_load_dwordx4 v[186:189], v139, s[22:23]
	global_load_dwordx4 v[190:193], v139, s[22:23] offset:64
	global_load_dwordx4 v[194:197], v139, s[22:23] offset:512
	global_load_dwordx4 v[198:201], v139, s[22:23] offset:576
	s_waitcnt vmcnt(16)
	v_pk_fma_f32 v[46:47], v[46:47], v[154:155], v[202:203]
	v_pk_fma_f32 v[48:49], v[48:49], v[156:157], v[204:205]
	v_pk_fma_f32 v[42:43], v[42:43], v[158:159], v[206:207]
	v_pk_fma_f32 v[44:45], v[44:45], v[160:161], v[208:209]
	v_pk_fma_f32 v[38:39], v[38:39], v[162:163], v[142:143]
	v_pk_fma_f32 v[40:41], v[40:41], v[164:165], v[144:145]
	v_pk_fma_f32 v[34:35], v[34:35], v[166:167], v[146:147]
	v_pk_fma_f32 v[36:37], v[36:37], v[168:169], v[148:149]
	global_store_dwordx4 v211, v[46:49], s[20:21]
	global_store_dwordx4 v211, v[42:45], s[20:21] offset:64
	global_store_dwordx4 v211, v[38:41], s[20:21] offset:512
	global_store_dwordx4 v211, v[34:37], s[20:21] offset:576
	s_waitcnt vmcnt(12)
	v_pk_fma_f32 v[30:31], v[30:31], v[154:155], v[170:171]
	v_pk_fma_f32 v[32:33], v[32:33], v[156:157], v[172:173]
	v_pk_fma_f32 v[26:27], v[26:27], v[158:159], v[174:175]
	v_pk_fma_f32 v[28:29], v[28:29], v[160:161], v[176:177]
	v_pk_fma_f32 v[22:23], v[22:23], v[162:163], v[178:179]
	v_pk_fma_f32 v[24:25], v[24:25], v[164:165], v[180:181]
	v_pk_fma_f32 v[18:19], v[18:19], v[166:167], v[182:183]
	v_pk_fma_f32 v[20:21], v[20:21], v[168:169], v[184:185]
	global_store_dwordx4 v220, v[30:33], s[20:21]
	global_store_dwordx4 v220, v[26:29], s[20:21] offset:64
	global_store_dwordx4 v220, v[22:25], s[20:21] offset:512
	global_store_dwordx4 v220, v[18:21], s[20:21] offset:576
	s_waitcnt vmcnt(8)
	v_pk_fma_f32 v[14:15], v[14:15], v[154:155], v[186:187]
	v_pk_fma_f32 v[16:17], v[16:17], v[156:157], v[188:189]
	v_pk_fma_f32 v[10:11], v[10:11], v[158:159], v[190:191]
	v_pk_fma_f32 v[12:13], v[12:13], v[160:161], v[192:193]
	v_pk_fma_f32 v[6:7], v[6:7], v[162:163], v[194:195]
	v_pk_fma_f32 v[8:9], v[8:9], v[164:165], v[196:197]
	v_pk_fma_f32 v[2:3], v[2:3], v[166:167], v[198:199]
	v_pk_fma_f32 v[4:5], v[4:5], v[168:169], v[200:201]
	global_store_dwordx4 v139, v[14:17], s[20:21]
	global_store_dwordx4 v139, v[10:13], s[20:21] offset:64
	global_store_dwordx4 v139, v[6:9], s[20:21] offset:512
	global_store_dwordx4 v139, v[2:5], s[20:21] offset:576
	v_mov_b32_e32 v170, v219
	s_mov_b32 s14, s0
	s_mov_b32 s16, s8
	s_mov_b64 s[20:21], s[12:13]
	s_mov_b64 s[18:19], s[10:11]
	s_and_b64 vcc, exec, s[4:5]
	s_cbranch_vccnz .LBB0_1156
	s_branch .LBB0_1120

; #define PG8_STAGE(bufoff, gbase, voff) do { _Pragma("unroll") for (int _i = 0; _i < 2; ++_i) \
;         __builtin_amdgcn_global_load_lds((const unsigned*)((const char*)(gbase) + (voff)[_i]), (LAS unsigned*)(lds + (bufoff) + ldsw + _i * 8192), 16, 0, 0); } while (0)
; #define PG8_LDA(dst, b, h) do { _Pragma("unroll") for (int m = 0; m < 4; ++m) _Pragma("unroll") for (int k = 0; k < 2; ++k) dst[m][k] = *(const LAS bf16x8*)(lds + PG8_SA(b, h) + aoff + m * 2048 + k * 1024); } while (0)
; #define PG8_LDB(dst, b, h) do { _Pragma("unroll") for (int n = 0; n < 2; ++n) _Pragma("unroll") for (int k = 0; k < 2; ++k) dst[n][k] = *(const LAS bf16x8*)(lds + PG8_SB(b, h) + boff + n * 2048 + k * 1024); } while (0)
; #define PG8_MMA(ai, bj, At, Bt) do { __builtin_amdgcn_s_setprio(1); _Pragma("unroll") for (int m = 0; m < 4; ++m) _Pragma("unroll") for (int n = 0; n < 2; ++n) _Pragma("unroll") for (int k = 0; k < 2; ++k) \
;         acc[ai][bj][m][n] = __builtin_amdgcn_mfma_f32_16x16x32_bf16(Bt[n][k], At[m][k], acc[ai][bj][m][n], 0, 0, 0); __builtin_amdgcn_s_setprio(0); } while (0)
; template <class Epi, class Sched>
; __device__ __forceinline__ void gemm_phase(LAS unsigned char* lds, const Gemm g, const Sched& S, const Epi& E) {
;     ...
;     for (;;) {
;         const bool has_next = S.next(ui + 1, nxt);
;         const char* nA = has_next ? (const char*)g.A + (size_t)nxt.pm * tstep : cA; const char* nB = has_next ? (const char*)g.Bt + (size_t)nxt.pn * tstep : cB;
;         for (int t = 0; t < nt; t += 2) {
;             const bool last = (t == nt - 2);
;             const char* a1 = cA + (size_t)(t + 1) * kstep;
;             const char* a2 = last ? nA : cA + (size_t)(t + 2) * kstep; const char* b2 = last ? nB : cB + (size_t)(t + 2) * kstep;
;             const char* a3 = a2 + kstep; const char* b3 = b2 + kstep;
;             if (last && has_next) S.a_ready(nxt);
;             PG8_LDB(B0, 0, 0); PG8_SCHED; PG8_LDA(At, 0, 0); PG8_STAGE(PG8_SA(1, 1), a1 + hstep, voffA);
;             PG8_WAIT_L(8); PG8_BAR; PG8_WAIT_L(0); PG8_MMA(0, 0, At, B0); PG8_BAR; PG8_SCHED;
;     ...
; #pragma unroll
;         for (int a = 0; a < 2; ++a)
; #pragma unroll
;             for (int b = 0; b < 2; ++b)
; #pragma unroll
;                 for (int m = 0; m < 4; ++m)
; #pragma unroll
;                     for (int n = 0; n < 2; ++n) acc[a][b][m][n] = (f32x4){0.f, 0.f, 0.f, 0.f};
.LBB0_1342:
	v_readlane_b32 s10, v253, 24
	v_readlane_b32 s11, v253, 25
	s_ashr_i32 s7, s6, 31
	s_mov_b32 s40, s23
	v_mov_b64_e32 v[2:3], s[10:11]
	v_cmp_lt_i64_e32 vcc, s[8:9], v[2:3]
	s_lshl_b64 s[8:9], s[6:7], 22
	s_add_u32 s8, s58, s8
	s_addc_u32 s9, s59, s9
	s_add_u32 s8, s8, s22
	s_addc_u32 s9, s9, 0
	s_and_b64 s[10:11], vcc, exec
	s_cselect_b32 s3, s9, s17
	s_cselect_b32 s7, s8, s16
	s_ashr_i32 s5, s4, 31
	s_lshl_b64 s[10:11], s[4:5], 22
	s_add_u32 s10, s25, s10
	s_addc_u32 s11, s27, s11
	s_add_u32 s10, s10, s22
	s_addc_u32 s11, s11, 0
	s_and_b64 s[20:21], vcc, exec
	s_cselect_b32 s5, s11, s19
	s_cselect_b32 s37, s10, s18
	s_add_u32 s38, s18, 0x100
	v_mov_b32_e32 v2, 0
	s_addc_u32 s39, s19, 0
	v_mov_b32_e32 v3, v2
	v_mov_b32_e32 v4, v2
	v_mov_b32_e32 v5, v2
	v_mov_b32_e32 v6, v2
	v_mov_b32_e32 v7, v2
	v_mov_b32_e32 v8, v2
	v_mov_b32_e32 v9, v2
	v_mov_b32_e32 v18, v2
	v_mov_b32_e32 v19, v2
	v_mov_b32_e32 v20, v2
	v_mov_b32_e32 v21, v2
	v_mov_b32_e32 v22, v2
	v_mov_b32_e32 v23, v2
	v_mov_b32_e32 v24, v2
	v_mov_b32_e32 v25, v2
	v_mov_b32_e32 v34, v2
	v_mov_b32_e32 v35, v2
	v_mov_b32_e32 v36, v2
	v_mov_b32_e32 v37, v2
	v_mov_b32_e32 v38, v2
	v_mov_b32_e32 v39, v2
	v_mov_b32_e32 v40, v2
	v_mov_b32_e32 v41, v2
	v_mov_b32_e32 v50, v2
	v_mov_b32_e32 v51, v2
	v_mov_b32_e32 v52, v2
	v_mov_b32_e32 v53, v2
	v_mov_b32_e32 v54, v2
	v_mov_b32_e32 v55, v2
	v_mov_b32_e32 v56, v2
	v_mov_b32_e32 v57, v2
	v_mov_b32_e32 v10, v2
	v_mov_b32_e32 v11, v2
	v_mov_b32_e32 v12, v2
	v_mov_b32_e32 v13, v2
	v_mov_b32_e32 v14, v2
	v_mov_b32_e32 v15, v2
	v_mov_b32_e32 v16, v2
	v_mov_b32_e32 v17, v2
	v_mov_b32_e32 v26, v2
	v_mov_b32_e32 v27, v2
	v_mov_b32_e32 v28, v2
	v_mov_b32_e32 v29, v2
	v_mov_b32_e32 v30, v2
	v_mov_b32_e32 v31, v2
	v_mov_b32_e32 v32, v2
	v_mov_b32_e32 v33, v2
	v_mov_b32_e32 v42, v2
	v_mov_b32_e32 v43, v2
	v_mov_b32_e32 v44, v2
	v_mov_b32_e32 v45, v2
	v_mov_b32_e32 v46, v2
	v_mov_b32_e32 v47, v2
	v_mov_b32_e32 v48, v2
	v_mov_b32_e32 v49, v2
	v_mov_b32_e32 v58, v2
	v_mov_b32_e32 v59, v2
	v_mov_b32_e32 v60, v2
	v_mov_b32_e32 v61, v2
	v_mov_b32_e32 v62, v2
	v_mov_b32_e32 v63, v2
	v_mov_b32_e32 v64, v2
	v_mov_b32_e32 v65, v2
	v_mov_b32_e32 v66, v2
	v_mov_b32_e32 v67, v2
	v_mov_b32_e32 v68, v2
	v_mov_b32_e32 v69, v2
	v_mov_b32_e32 v70, v2
	v_mov_b32_e32 v71, v2
	v_mov_b32_e32 v72, v2
	v_mov_b32_e32 v73, v2
	v_mov_b32_e32 v82, v2
	v_mov_b32_e32 v83, v2
	v_mov_b32_e32 v84, v2
	v_mov_b32_e32 v85, v2
	v_mov_b32_e32 v86, v2
	v_mov_b32_e32 v87, v2
	v_mov_b32_e32 v88, v2
	v_mov_b32_e32 v89, v2
	v_mov_b32_e32 v98, v2
	v_mov_b32_e32 v99, v2
	v_mov_b32_e32 v100, v2
	v_mov_b32_e32 v101, v2
	v_mov_b32_e32 v102, v2
	v_mov_b32_e32 v103, v2
	v_mov_b32_e32 v104, v2
	v_mov_b32_e32 v105, v2
	v_mov_b32_e32 v114, v2
	v_mov_b32_e32 v115, v2
	v_mov_b32_e32 v116, v2
	v_mov_b32_e32 v117, v2
	v_mov_b32_e32 v118, v2
	v_mov_b32_e32 v119, v2
	v_mov_b32_e32 v120, v2
	v_mov_b32_e32 v121, v2
	v_mov_b32_e32 v74, v2
	v_mov_b32_e32 v75, v2
	v_mov_b32_e32 v76, v2
	v_mov_b32_e32 v77, v2
	v_mov_b32_e32 v78, v2
	v_mov_b32_e32 v79, v2
	v_mov_b32_e32 v80, v2
	v_mov_b32_e32 v81, v2
	v_mov_b32_e32 v90, v2
	v_mov_b32_e32 v91, v2
	v_mov_b32_e32 v92, v2
	v_mov_b32_e32 v93, v2
	v_mov_b32_e32 v94, v2
	v_mov_b32_e32 v95, v2
	v_mov_b32_e32 v96, v2
	v_mov_b32_e32 v97, v2
	v_mov_b32_e32 v106, v2
	v_mov_b32_e32 v107, v2
	v_mov_b32_e32 v108, v2
	v_mov_b32_e32 v109, v2
	v_mov_b32_e32 v110, v2
	v_mov_b32_e32 v111, v2
	v_mov_b32_e32 v112, v2
	v_mov_b32_e32 v113, v2
	v_mov_b32_e32 v122, v2
	v_mov_b32_e32 v123, v2
	v_mov_b32_e32 v124, v2
	v_mov_b32_e32 v125, v2
	v_mov_b32_e32 v126, v2
	v_mov_b32_e32 v127, v2
	v_mov_b32_e32 v128, v2
	v_mov_b32_e32 v129, v2
	v_readlane_b32 s42, v253, 6
	s_mov_b64 s[44:45], 0x80
	v_add_u32_e32 v209, 0x14000, v139
	v_add_u32_e32 v210, 0x18000, v139
	v_add_u32_e32 v211, 0x1c000, v139
	v_add_u32_e32 v208, s42, v139
.LBB0_1343:
	s_nop 0
	ds_read_b128 v[142:145], v208
	ds_read_b128 v[146:149], v208 offset:1024
	ds_read_b128 v[150:153], v208 offset:2048
	ds_read_b128 v[154:157], v208 offset:3072
	s_add_u32 s18, s16, 0x100
	s_addc_u32 s19, s17, 0
	s_cmpk_eq_i32 s40, 0x7c
	s_cselect_b32 s23, s3, s19
	s_cselect_b32 s22, s7, s18
	s_cselect_b32 s21, s5, s39
	s_cselect_b32 s20, s37, s38
	s_add_i32 m0, s13, 0xc000
	ds_read_b128 v[158:161], v141
	ds_read_b128 v[162:165], v141 offset:1024
	ds_read_b128 v[166:169], v141 offset:2048
	ds_read_b128 v[170:173], v141 offset:3072
	ds_read_b128 v[174:177], v141 offset:4096
	ds_read_b128 v[178:181], v141 offset:5120
	ds_read_b128 v[182:185], v141 offset:6144
	ds_read_b128 v[186:189], v141 offset:7168
	global_load_lds_dwordx4 v132, s[16:17]
	s_add_i32 m0, s13, 0xe000
	s_nop 0
	global_load_lds_dwordx4 v134, s[16:17]
	s_waitcnt lgkmcnt(8)
	s_barrier
	s_waitcnt lgkmcnt(0)
	v_mfma_f32_16x16x32_bf16 v[126:129], v[142:145], v[158:161], v[126:129]
	v_mfma_f32_16x16x32_bf16 v[122:125], v[150:153], v[158:161], v[122:125]
	v_mfma_f32_16x16x32_bf16 v[110:113], v[142:145], v[166:169], v[110:113]
	v_mfma_f32_16x16x32_bf16 v[106:109], v[150:153], v[166:169], v[106:109]
	v_mfma_f32_16x16x32_bf16 v[94:97], v[142:145], v[174:177], v[94:97]
	v_mfma_f32_16x16x32_bf16 v[90:93], v[150:153], v[174:177], v[90:93]
	v_mfma_f32_16x16x32_bf16 v[78:81], v[142:145], v[182:185], v[78:81]
	v_mfma_f32_16x16x32_bf16 v[74:77], v[150:153], v[182:185], v[74:77]
	v_mfma_f32_16x16x32_bf16 v[126:129], v[146:149], v[162:165], v[126:129]
	v_mfma_f32_16x16x32_bf16 v[122:125], v[154:157], v[162:165], v[122:125]
	v_mfma_f32_16x16x32_bf16 v[110:113], v[146:149], v[170:173], v[110:113]
	v_mfma_f32_16x16x32_bf16 v[106:109], v[154:157], v[170:173], v[106:109]
	v_mfma_f32_16x16x32_bf16 v[94:97], v[146:149], v[178:181], v[94:97]
	v_mfma_f32_16x16x32_bf16 v[90:93], v[154:157], v[178:181], v[90:93]
	v_mfma_f32_16x16x32_bf16 v[78:81], v[146:149], v[186:189], v[78:81]
	v_mfma_f32_16x16x32_bf16 v[74:77], v[154:157], v[186:189], v[74:77]
	s_barrier
; #define PG8_STAGE(bufoff, gbase, voff) do { _Pragma("unroll") for (int _i = 0; _i < 2; ++_i) \
;         __builtin_amdgcn_global_load_lds((const unsigned*)((const char*)(gbase) + (voff)[_i]), (LAS unsigned*)(lds + (bufoff) + ldsw + _i * 8192), 16, 0, 0); } while (0)
; #define PG8_LDA(dst, b, h) do { _Pragma("unroll") for (int m = 0; m < 4; ++m) _Pragma("unroll") for (int k = 0; k < 2; ++k) dst[m][k] = *(const LAS bf16x8*)(lds + PG8_SA(b, h) + aoff + m * 2048 + k * 1024); } while (0)
; #define PG8_LDB(dst, b, h) do { _Pragma("unroll") for (int n = 0; n < 2; ++n) _Pragma("unroll") for (int k = 0; k < 2; ++k) dst[n][k] = *(const LAS bf16x8*)(lds + PG8_SB(b, h) + boff + n * 2048 + k * 1024); } while (0)
; #define PG8_MMA(ai, bj, At, Bt) do { __builtin_amdgcn_s_setprio(1); _Pragma("unroll") for (int m = 0; m < 4; ++m) _Pragma("unroll") for (int n = 0; n < 2; ++n) _Pragma("unroll") for (int k = 0; k < 2; ++k) \
;         acc[ai][bj][m][n] = __builtin_amdgcn_mfma_f32_16x16x32_bf16(Bt[n][k], At[m][k], acc[ai][bj][m][n], 0, 0, 0); __builtin_amdgcn_s_setprio(0); } while (0)
; #define PG8_WAIT_V(n) asm volatile("s_waitcnt vmcnt(" #n ")" ::: "memory")
; #define PG8_WAIT_L(n) asm volatile("s_waitcnt lgkmcnt(" #n ")" ::: "memory")
; #define PG8_BAR __builtin_amdgcn_s_barrier()
; #define PG8_SCHED __builtin_amdgcn_sched_barrier(0)
; template <class Epi, class Sched>
; __device__ __forceinline__ void gemm_phase(LAS unsigned char* lds, const Gemm g, const Sched& S, const Epi& E) {
;     ...
;             PG8_WAIT_L(8); PG8_BAR; PG8_WAIT_L(0); PG8_MMA(0, 0, At, B0); PG8_BAR; PG8_SCHED;
;             PG8_LDB(B1, 0, 1); PG8_STAGE(PG8_SB(0, 0), b2, voffB);
;             PG8_BAR; PG8_WAIT_L(0); PG8_MMA(0, 1, At, B1); PG8_BAR;
;             PG8_LDA(At, 0, 1); PG8_STAGE(PG8_SA(0, 0), a2, voffA);
;             PG8_BAR; PG8_WAIT_L(0); PG8_MMA(1, 0, At, B0); PG8_BAR; PG8_SCHED;
;             PG8_STAGE(PG8_SB(0, 1), b2 + hstep, voffB);
;             PG8_WAIT_V(6); PG8_BAR; PG8_MMA(1, 1, At, B1); PG8_BAR;
;             PG8_LDB(B0, 1, 0); PG8_SCHED; PG8_LDA(At, 1, 0); PG8_STAGE(PG8_SA(0, 1), a2 + hstep, voffA);
;             PG8_WAIT_L(8); PG8_BAR; PG8_WAIT_L(0); PG8_MMA(0, 0, At, B0); PG8_BAR; PG8_SCHED;
	s_add_i32 s41, 0, 0x14000
	s_add_i32 s16, s42, s28
	ds_read_b128 v[190:193], v209
	ds_read_b128 v[194:197], v209 offset:1024
	ds_read_b128 v[198:201], v209 offset:2048
	ds_read_b128 v[202:205], v209 offset:3072
	s_mov_b32 m0, s16
	s_nop 0
	global_load_lds_dwordx4 v0, s[20:21]
	s_add_i32 m0, s16, 0x2000
	s_nop 0
	global_load_lds_dwordx4 v130, s[20:21]
	s_barrier
	s_waitcnt lgkmcnt(0)
	v_mfma_f32_16x16x32_bf16 v[118:121], v[190:193], v[158:161], v[118:121]
	v_mfma_f32_16x16x32_bf16 v[114:117], v[198:201], v[158:161], v[114:117]
	v_mfma_f32_16x16x32_bf16 v[102:105], v[190:193], v[166:169], v[102:105]
	v_mfma_f32_16x16x32_bf16 v[98:101], v[198:201], v[166:169], v[98:101]
	v_mfma_f32_16x16x32_bf16 v[86:89], v[190:193], v[174:177], v[86:89]
	v_mfma_f32_16x16x32_bf16 v[82:85], v[198:201], v[174:177], v[82:85]
	v_mfma_f32_16x16x32_bf16 v[70:73], v[190:193], v[182:185], v[70:73]
	v_mfma_f32_16x16x32_bf16 v[66:69], v[198:201], v[182:185], v[66:69]
	v_mfma_f32_16x16x32_bf16 v[118:121], v[194:197], v[162:165], v[118:121]
	v_mfma_f32_16x16x32_bf16 v[114:117], v[202:205], v[162:165], v[114:117]
	v_mfma_f32_16x16x32_bf16 v[102:105], v[194:197], v[170:173], v[102:105]
	v_mfma_f32_16x16x32_bf16 v[98:101], v[202:205], v[170:173], v[98:101]
	v_mfma_f32_16x16x32_bf16 v[86:89], v[194:197], v[178:181], v[86:89]
	v_mfma_f32_16x16x32_bf16 v[82:85], v[202:205], v[178:181], v[82:85]
	v_mfma_f32_16x16x32_bf16 v[70:73], v[194:197], v[186:189], v[70:73]
	v_mfma_f32_16x16x32_bf16 v[66:69], v[202:205], v[186:189], v[66:69]
	s_mov_b32 m0, s13
	s_barrier
	ds_read_b128 v[158:161], v141 offset:16384
	ds_read_b128 v[162:165], v141 offset:17408
	ds_read_b128 v[166:169], v141 offset:18432
	ds_read_b128 v[170:173], v141 offset:19456
	ds_read_b128 v[174:177], v141 offset:20480
	ds_read_b128 v[178:181], v141 offset:21504
	ds_read_b128 v[182:185], v141 offset:22528
	ds_read_b128 v[186:189], v141 offset:23552
	global_load_lds_dwordx4 v0, s[22:23]
	s_mov_b32 m0, s15
	s_nop 0
	global_load_lds_dwordx4 v130, s[22:23]
	s_barrier
	s_waitcnt lgkmcnt(0)
	v_mfma_f32_16x16x32_bf16 v[62:65], v[142:145], v[158:161], v[62:65]
	v_mfma_f32_16x16x32_bf16 v[58:61], v[150:153], v[158:161], v[58:61]
	v_mfma_f32_16x16x32_bf16 v[46:49], v[142:145], v[166:169], v[46:49]
	v_mfma_f32_16x16x32_bf16 v[42:45], v[150:153], v[166:169], v[42:45]
	v_mfma_f32_16x16x32_bf16 v[30:33], v[142:145], v[174:177], v[30:33]
	v_mfma_f32_16x16x32_bf16 v[26:29], v[150:153], v[174:177], v[26:29]
	v_mfma_f32_16x16x32_bf16 v[14:17], v[142:145], v[182:185], v[14:17]
	v_mfma_f32_16x16x32_bf16 v[10:13], v[150:153], v[182:185], v[10:13]
	v_mfma_f32_16x16x32_bf16 v[62:65], v[146:149], v[162:165], v[62:65]
	v_mfma_f32_16x16x32_bf16 v[58:61], v[154:157], v[162:165], v[58:61]
	v_mfma_f32_16x16x32_bf16 v[46:49], v[146:149], v[170:173], v[46:49]
	v_mfma_f32_16x16x32_bf16 v[42:45], v[154:157], v[170:173], v[42:45]
	v_mfma_f32_16x16x32_bf16 v[30:33], v[146:149], v[178:181], v[30:33]
	v_mfma_f32_16x16x32_bf16 v[26:29], v[154:157], v[178:181], v[26:29]
	v_mfma_f32_16x16x32_bf16 v[14:17], v[146:149], v[186:189], v[14:17]
	v_mfma_f32_16x16x32_bf16 v[10:13], v[154:157], v[186:189], v[10:13]
	s_barrier
	s_add_u32 s16, s20, 0x200000
	s_addc_u32 s17, s21, 0
	s_add_i32 s41, s41, s28
	s_mov_b32 m0, s41
	s_nop 0
	global_load_lds_dwordx4 v0, s[16:17]
	s_add_i32 m0, s41, 0x2000
	s_nop 0
	global_load_lds_dwordx4 v130, s[16:17]
	s_waitcnt vmcnt(6)
	s_barrier
	v_mfma_f32_16x16x32_bf16 v[54:57], v[190:193], v[158:161], v[54:57]
	v_mfma_f32_16x16x32_bf16 v[50:53], v[198:201], v[158:161], v[50:53]
	v_mfma_f32_16x16x32_bf16 v[38:41], v[190:193], v[166:169], v[38:41]
	v_mfma_f32_16x16x32_bf16 v[34:37], v[198:201], v[166:169], v[34:37]
	v_mfma_f32_16x16x32_bf16 v[22:25], v[190:193], v[174:177], v[22:25]
	v_mfma_f32_16x16x32_bf16 v[18:21], v[198:201], v[174:177], v[18:21]
	v_mfma_f32_16x16x32_bf16 v[6:9], v[190:193], v[182:185], v[6:9]
	v_mfma_f32_16x16x32_bf16 v[2:5], v[198:201], v[182:185], v[2:5]
	v_mfma_f32_16x16x32_bf16 v[54:57], v[194:197], v[162:165], v[54:57]
	v_mfma_f32_16x16x32_bf16 v[50:53], v[202:205], v[162:165], v[50:53]
	v_mfma_f32_16x16x32_bf16 v[38:41], v[194:197], v[170:173], v[38:41]
	v_mfma_f32_16x16x32_bf16 v[34:37], v[202:205], v[170:173], v[34:37]
	v_mfma_f32_16x16x32_bf16 v[22:25], v[194:197], v[178:181], v[22:25]
	v_mfma_f32_16x16x32_bf16 v[18:21], v[202:205], v[178:181], v[18:21]
	v_mfma_f32_16x16x32_bf16 v[6:9], v[194:197], v[186:189], v[6:9]
	v_mfma_f32_16x16x32_bf16 v[2:5], v[202:205], v[186:189], v[2:5]
	s_add_i32 s41, 0, 0x18000
	s_barrier
	ds_read_b128 v[142:145], v210
	ds_read_b128 v[146:149], v210 offset:1024
	ds_read_b128 v[150:153], v210 offset:2048
	ds_read_b128 v[154:157], v210 offset:3072
	s_add_u32 s16, s22, 0x200000
	s_addc_u32 s17, s23, 0
	s_mov_b32 m0, s29
	ds_read_b128 v[158:161], v141 offset:32768
	ds_read_b128 v[162:165], v141 offset:33792
	ds_read_b128 v[166:169], v141 offset:34816
	ds_read_b128 v[170:173], v141 offset:35840
	ds_read_b128 v[174:177], v141 offset:36864
	ds_read_b128 v[178:181], v141 offset:37888
	ds_read_b128 v[182:185], v141 offset:38912
	ds_read_b128 v[186:189], v141 offset:39936
	global_load_lds_dwordx4 v0, s[16:17]
	s_mov_b32 m0, s30
	s_add_u32 s44, s22, 0x80
	s_addc_u32 s45, s23, 0
	global_load_lds_dwordx4 v130, s[16:17]
	s_waitcnt lgkmcnt(8)
	s_barrier
; #define PG8_STAGE(bufoff, gbase, voff) do { _Pragma("unroll") for (int _i = 0; _i < 2; ++_i) \
;         __builtin_amdgcn_global_load_lds((const unsigned*)((const char*)(gbase) + (voff)[_i]), (LAS unsigned*)(lds + (bufoff) + ldsw + _i * 8192), 16, 0, 0); } while (0)
; #define PG8_LDA(dst, b, h) do { _Pragma("unroll") for (int m = 0; m < 4; ++m) _Pragma("unroll") for (int k = 0; k < 2; ++k) dst[m][k] = *(const LAS bf16x8*)(lds + PG8_SA(b, h) + aoff + m * 2048 + k * 1024); } while (0)
; #define PG8_LDB(dst, b, h) do { _Pragma("unroll") for (int n = 0; n < 2; ++n) _Pragma("unroll") for (int k = 0; k < 2; ++k) dst[n][k] = *(const LAS bf16x8*)(lds + PG8_SB(b, h) + boff + n * 2048 + k * 1024); } while (0)
; #define PG8_MMA(ai, bj, At, Bt) do { __builtin_amdgcn_s_setprio(1); _Pragma("unroll") for (int m = 0; m < 4; ++m) _Pragma("unroll") for (int n = 0; n < 2; ++n) _Pragma("unroll") for (int k = 0; k < 2; ++k) \
;         acc[ai][bj][m][n] = __builtin_amdgcn_mfma_f32_16x16x32_bf16(Bt[n][k], At[m][k], acc[ai][bj][m][n], 0, 0, 0); __builtin_amdgcn_s_setprio(0); } while (0)
; #define PG8_WAIT_L(n) asm volatile("s_waitcnt lgkmcnt(" #n ")" ::: "memory")
; #define PG8_BAR __builtin_amdgcn_s_barrier()
; #define PG8_SCHED __builtin_amdgcn_sched_barrier(0)
; template <class Epi, class Sched>
; __device__ __forceinline__ void gemm_phase(LAS unsigned char* lds, const Gemm g, const Sched& S, const Epi& E) {
;     ...
;             PG8_WAIT_L(8); PG8_BAR; PG8_WAIT_L(0); PG8_MMA(0, 0, At, B0); PG8_BAR; PG8_SCHED;
;             PG8_LDB(B1, 1, 1); PG8_STAGE(PG8_SB(1, 0), b3, voffB);
;             PG8_BAR; PG8_WAIT_L(0); PG8_MMA(0, 1, At, B1); PG8_BAR;
;             PG8_LDA(At, 1, 1); PG8_STAGE(PG8_SA(1, 0), a3, voffA);
;             PG8_BAR; PG8_WAIT_L(0); PG8_MMA(1, 0, At, B0); PG8_BAR; PG8_SCHED;
	s_waitcnt lgkmcnt(0)
	v_mfma_f32_16x16x32_bf16 v[126:129], v[142:145], v[158:161], v[126:129]
	v_mfma_f32_16x16x32_bf16 v[122:125], v[150:153], v[158:161], v[122:125]
	v_mfma_f32_16x16x32_bf16 v[110:113], v[142:145], v[166:169], v[110:113]
	v_mfma_f32_16x16x32_bf16 v[106:109], v[150:153], v[166:169], v[106:109]
	v_mfma_f32_16x16x32_bf16 v[94:97], v[142:145], v[174:177], v[94:97]
	v_mfma_f32_16x16x32_bf16 v[90:93], v[150:153], v[174:177], v[90:93]
	v_mfma_f32_16x16x32_bf16 v[78:81], v[142:145], v[182:185], v[78:81]
	v_mfma_f32_16x16x32_bf16 v[74:77], v[150:153], v[182:185], v[74:77]
	v_mfma_f32_16x16x32_bf16 v[126:129], v[146:149], v[162:165], v[126:129]
	v_mfma_f32_16x16x32_bf16 v[122:125], v[154:157], v[162:165], v[122:125]
	v_mfma_f32_16x16x32_bf16 v[110:113], v[146:149], v[170:173], v[110:113]
	v_mfma_f32_16x16x32_bf16 v[106:109], v[154:157], v[170:173], v[106:109]
	v_mfma_f32_16x16x32_bf16 v[94:97], v[146:149], v[178:181], v[94:97]
	v_mfma_f32_16x16x32_bf16 v[90:93], v[154:157], v[178:181], v[90:93]
	v_mfma_f32_16x16x32_bf16 v[78:81], v[146:149], v[186:189], v[78:81]
	v_mfma_f32_16x16x32_bf16 v[74:77], v[154:157], v[186:189], v[74:77]
	s_barrier
	s_add_i32 s22, 0, 0x1c000
	s_add_i32 s23, s41, s28
	s_add_u32 s16, s20, 0x80
	s_addc_u32 s17, s21, 0
	s_mov_b32 m0, s23
	ds_read_b128 v[190:193], v211
	ds_read_b128 v[194:197], v211 offset:1024
	ds_read_b128 v[198:201], v211 offset:2048
	ds_read_b128 v[202:205], v211 offset:3072
	global_load_lds_dwordx4 v0, s[16:17]
	s_add_i32 m0, s23, 0x2000
	s_nop 0
	global_load_lds_dwordx4 v130, s[16:17]
	s_barrier
	s_waitcnt lgkmcnt(0)
	v_mfma_f32_16x16x32_bf16 v[118:121], v[190:193], v[158:161], v[118:121]
	v_mfma_f32_16x16x32_bf16 v[114:117], v[198:201], v[158:161], v[114:117]
	v_mfma_f32_16x16x32_bf16 v[102:105], v[190:193], v[166:169], v[102:105]
	v_mfma_f32_16x16x32_bf16 v[98:101], v[198:201], v[166:169], v[98:101]
	v_mfma_f32_16x16x32_bf16 v[86:89], v[190:193], v[174:177], v[86:89]
	v_mfma_f32_16x16x32_bf16 v[82:85], v[198:201], v[174:177], v[82:85]
	v_mfma_f32_16x16x32_bf16 v[70:73], v[190:193], v[182:185], v[70:73]
	v_mfma_f32_16x16x32_bf16 v[66:69], v[198:201], v[182:185], v[66:69]
	v_mfma_f32_16x16x32_bf16 v[118:121], v[194:197], v[162:165], v[118:121]
	v_mfma_f32_16x16x32_bf16 v[114:117], v[202:205], v[162:165], v[114:117]
	v_mfma_f32_16x16x32_bf16 v[102:105], v[194:197], v[170:173], v[102:105]
	v_mfma_f32_16x16x32_bf16 v[98:101], v[202:205], v[170:173], v[98:101]
	v_mfma_f32_16x16x32_bf16 v[86:89], v[194:197], v[178:181], v[86:89]
	v_mfma_f32_16x16x32_bf16 v[82:85], v[202:205], v[178:181], v[82:85]
	v_mfma_f32_16x16x32_bf16 v[70:73], v[194:197], v[186:189], v[70:73]
	v_mfma_f32_16x16x32_bf16 v[66:69], v[202:205], v[186:189], v[66:69]
	s_mov_b32 m0, s34
	s_barrier
	ds_read_b128 v[158:161], v141 offset:49152
	ds_read_b128 v[162:165], v141 offset:50176
	ds_read_b128 v[166:169], v141 offset:51200
	ds_read_b128 v[170:173], v141 offset:52224
	ds_read_b128 v[174:177], v141 offset:53248
	ds_read_b128 v[178:181], v141 offset:54272
	ds_read_b128 v[182:185], v141 offset:55296
	ds_read_b128 v[186:189], v141 offset:56320
	global_load_lds_dwordx4 v0, s[44:45]
	s_mov_b32 m0, s35
	s_nop 0
	global_load_lds_dwordx4 v130, s[44:45]
	s_barrier
	s_waitcnt lgkmcnt(0)
	v_mfma_f32_16x16x32_bf16 v[62:65], v[142:145], v[158:161], v[62:65]
	v_mfma_f32_16x16x32_bf16 v[58:61], v[150:153], v[158:161], v[58:61]
	v_mfma_f32_16x16x32_bf16 v[46:49], v[142:145], v[166:169], v[46:49]
	v_mfma_f32_16x16x32_bf16 v[42:45], v[150:153], v[166:169], v[42:45]
	v_mfma_f32_16x16x32_bf16 v[30:33], v[142:145], v[174:177], v[30:33]
	v_mfma_f32_16x16x32_bf16 v[26:29], v[150:153], v[174:177], v[26:29]
	v_mfma_f32_16x16x32_bf16 v[14:17], v[142:145], v[182:185], v[14:17]
	v_mfma_f32_16x16x32_bf16 v[10:13], v[150:153], v[182:185], v[10:13]
	v_mfma_f32_16x16x32_bf16 v[62:65], v[146:149], v[162:165], v[62:65]
	v_mfma_f32_16x16x32_bf16 v[58:61], v[154:157], v[162:165], v[58:61]
	v_mfma_f32_16x16x32_bf16 v[46:49], v[146:149], v[170:173], v[46:49]
	v_mfma_f32_16x16x32_bf16 v[42:45], v[154:157], v[170:173], v[42:45]
	v_mfma_f32_16x16x32_bf16 v[30:33], v[146:149], v[178:181], v[30:33]
	v_mfma_f32_16x16x32_bf16 v[26:29], v[154:157], v[178:181], v[26:29]
	v_mfma_f32_16x16x32_bf16 v[14:17], v[146:149], v[186:189], v[14:17]
	v_mfma_f32_16x16x32_bf16 v[10:13], v[154:157], v[186:189], v[10:13]
	s_barrier
; #define PG8_STAGE(bufoff, gbase, voff) do { _Pragma("unroll") for (int _i = 0; _i < 2; ++_i) \
;         __builtin_amdgcn_global_load_lds((const unsigned*)((const char*)(gbase) + (voff)[_i]), (LAS unsigned*)(lds + (bufoff) + ldsw + _i * 8192), 16, 0, 0); } while (0)
; #define PG8_MMA(ai, bj, At, Bt) do { __builtin_amdgcn_s_setprio(1); _Pragma("unroll") for (int m = 0; m < 4; ++m) _Pragma("unroll") for (int n = 0; n < 2; ++n) _Pragma("unroll") for (int k = 0; k < 2; ++k) \
;         acc[ai][bj][m][n] = __builtin_amdgcn_mfma_f32_16x16x32_bf16(Bt[n][k], At[m][k], acc[ai][bj][m][n], 0, 0, 0); __builtin_amdgcn_s_setprio(0); } while (0)
; #define PG8_WAIT_V(n) asm volatile("s_waitcnt vmcnt(" #n ")" ::: "memory")
; #define PG8_WAIT_L(n) asm volatile("s_waitcnt lgkmcnt(" #n ")" ::: "memory")
; #define PG8_BAR __builtin_amdgcn_s_barrier()
; #define PG8_SCHED __builtin_amdgcn_sched_barrier(0)
; template <class Epi, class Sched>
; __device__ __forceinline__ void gemm_phase(LAS unsigned char* lds, const Gemm g, const Sched& S, const Epi& E) {
;     ...
;             PG8_BAR; PG8_WAIT_L(0); PG8_MMA(1, 0, At, B0); PG8_BAR; PG8_SCHED;
;             PG8_STAGE(PG8_SB(1, 1), b3 + hstep, voffB);
;             PG8_WAIT_V(6); PG8_BAR; PG8_MMA(1, 1, At, B1); PG8_BAR;
;     __device__ __forceinline__ void operator()(const f32x4 (&acc)[2][2][4][2], const pg8::Unit& u, int wr, int wc, int fr, int fq) const {
;         const int row0 = u.pm * 256 + wr * 64 + fr; const int col0 = u.pn * 256 + wc * 32 + 4 * fq;
; #pragma unroll
;         for (int ai = 0; ai < 2; ++ai)
; #pragma unroll
;             for (int m = 0; m < 4; ++m) { const int row = row0 + ai * 128 + m * 16;
;                 const float* ip; float* op; int b;
;                 if (row < ML_ROWS) { b = row >> 11; ip = xi + (size_t)row * D; op = xo + (size_t)row * D; }
;                 else { b = 8; ip = ci + (size_t)(row - ML_ROWS) * D; op = co + (size_t)(row - ML_ROWS) * D; }
;                 const float* gp = mod + (size_t)b * 12288 + slot * 2048;
	s_add_u32 s16, s20, 0x200080
	s_addc_u32 s17, s21, 0
	s_add_i32 s20, s22, s28
	s_mov_b32 m0, s20
	s_nop 0
	global_load_lds_dwordx4 v0, s[16:17]
	s_add_i32 m0, s20, 0x2000
	s_nop 0
	global_load_lds_dwordx4 v130, s[16:17]
	s_waitcnt vmcnt(6)
	s_barrier
	v_mfma_f32_16x16x32_bf16 v[54:57], v[190:193], v[158:161], v[54:57]
	v_mfma_f32_16x16x32_bf16 v[50:53], v[198:201], v[158:161], v[50:53]
	v_mfma_f32_16x16x32_bf16 v[38:41], v[190:193], v[166:169], v[38:41]
	v_mfma_f32_16x16x32_bf16 v[34:37], v[198:201], v[166:169], v[34:37]
	v_mfma_f32_16x16x32_bf16 v[22:25], v[190:193], v[174:177], v[22:25]
	v_mfma_f32_16x16x32_bf16 v[18:21], v[198:201], v[174:177], v[18:21]
	v_mfma_f32_16x16x32_bf16 v[6:9], v[190:193], v[182:185], v[6:9]
	v_mfma_f32_16x16x32_bf16 v[2:5], v[198:201], v[182:185], v[2:5]
	v_mfma_f32_16x16x32_bf16 v[54:57], v[194:197], v[162:165], v[54:57]
	v_mfma_f32_16x16x32_bf16 v[50:53], v[202:205], v[162:165], v[50:53]
	v_mfma_f32_16x16x32_bf16 v[38:41], v[194:197], v[170:173], v[38:41]
	v_mfma_f32_16x16x32_bf16 v[34:37], v[202:205], v[170:173], v[34:37]
	v_mfma_f32_16x16x32_bf16 v[22:25], v[194:197], v[178:181], v[22:25]
	v_mfma_f32_16x16x32_bf16 v[18:21], v[202:205], v[178:181], v[18:21]
	v_mfma_f32_16x16x32_bf16 v[6:9], v[194:197], v[186:189], v[6:9]
	v_mfma_f32_16x16x32_bf16 v[2:5], v[202:205], v[186:189], v[2:5]
	s_add_i32 s40, s40, 2
	s_add_u32 s38, s38, 0x100
	s_addc_u32 s39, s39, 0
	s_cmpk_gt_u32 s40, 0x7d
	s_mov_b64 s[16:17], s[18:19]
	s_barrier
	s_cbranch_scc0 .LBB0_1343
	s_lshl_b32 s3, s14, 8
	s_add_i32 s3, s3, s31
	v_readlane_b32 s40, v251, 0
	v_readlane_b32 s41, v251, 1
	v_readlane_b32 s42, v251, 2
	v_readlane_b32 s43, v251, 3
	v_readlane_b32 s44, v251, 4
	v_readlane_b32 s45, v251, 5
	v_readlane_b32 s46, v251, 6
	v_readlane_b32 s47, v251, 7
	v_readlane_b32 s18, v254, 2
	v_readlane_b32 s19, v254, 3
	s_add_i32 s5, s3, 0xffffc000
	s_ashr_i32 s7, s3, 11
	s_cmpk_lt_i32 s3, 0x4000
	s_cselect_b32 s20, s42, s60
	s_cselect_b32 s21, s43, s61
	s_cselect_b32 s5, s3, s5
	s_cselect_b32 s7, s7, 8
	s_mul_i32 s7, s7, 0xc000
	s_add_u32 s18, s18, s7
	s_addc_u32 s19, s19, 0
	s_add_u32 s18, s18, 0xa000
	s_addc_u32 s19, s19, 0
	v_add_u32_e32 v136, s5, v138
	v_lshl_or_b32 v137, s12, 8, v140
	v_lshlrev_b32_e32 v137, 2, v137
	v_lshl_or_b32 v136, v136, 13, v137
	s_mov_b32 s12, s4
	s_mov_b32 s14, s6
	s_cmp_lg_u32 s36, 3
	s_cbranch_scc1 .Lsk_normal
	v_readlane_b32 s5, v253, 24
	s_cmpk_lg_u32 s46, 0x100
	s_cbranch_scc1 .Lsk_normal
	s_cmpk_lg_u32 s5, 0x240
	s_cbranch_scc1 .Lsk_normal
	s_and_b32 s7, s54, 3
	s_lshr_b32 s5, s54, 2
	s_lshr_b32 s3, s24, 6
	s_lshl_b32 s23, s5, 3
	s_add_i32 s23, s23, s3
	s_lshl_b32 s23, s23, 2
	v_readlane_b32 s38, v251, 10
	v_readlane_b32 s39, v251, 11
	s_add_u32 s38, s38, s23
	s_addc_u32 s39, s39, 0
	s_add_u32 s38, s38, 0x3700
	s_addc_u32 s39, s39, 0
	v_readlane_b32 s16, v251, 4
	v_readlane_b32 s17, v251, 5
	s_lshl_b32 s5, s5, 20
	s_add_u32 s16, s16, 0x24000000
	s_addc_u32 s17, s17, 0
	s_add_u32 s16, s16, s5
	s_addc_u32 s17, s17, 0
	v_add_u32_e32 v142, s31, v138
	v_lshlrev_b32_e32 v143, 2, v140
	v_lshl_or_b32 v142, v142, 10, v143
	global_load_dwordx4 v[146:149], v137, s[18:19]
	global_load_dwordx4 v[150:153], v137, s[18:19] offset:64
	global_load_dwordx4 v[154:157], v137, s[18:19] offset:512
	global_load_dwordx4 v[158:161], v137, s[18:19] offset:576
	s_cmp_eq_u32 s7, 1
	s_cbranch_scc1 .Lsk_v1
	s_cmp_eq_u32 s7, 2
	s_cbranch_scc1 .Lsk_v2
	s_cmp_eq_u32 s7, 3
	s_cbranch_scc1 .Lsk_v3
